# HGRN: output tile computed transposed (MFMA operands swapped) so each lane stores one 8-byte row piece instead of four 2-byte stores; counted vmcnt adjusted (v34 + ot)
# speedup vs baseline: 1.0051x; 1.0050x over previous
.LBB0_943:
	s_nop 2
	v_mov_b32_e32 v148, v32
	v_mov_b32_e32 v149, v33
	v_mov_b32_e32 v150, v34
	v_mov_b32_e32 v151, v35
	s_waitcnt vmcnt(8)
	v_mov_b32_e32 v44, v200
	s_waitcnt vmcnt(6)
	v_mov_b32_e32 v42, v202
	s_waitcnt vmcnt(4)
	v_mov_b32_e32 v40, v204
	s_waitcnt vmcnt(2)
	v_mov_b32_e32 v38, v206
	v_mov_b32_e32 v45, v199
	v_mov_b32_e32 v43, v201
	v_mov_b32_e32 v41, v203
	v_mov_b32_e32 v39, v205
	s_waitcnt vmcnt(1)
	v_mov_b64_e32 v[36:37], v[152:153]
	s_bitcmp1_b32 s61, 0
	s_cselect_b32 s62, 0x5800, 0
	s_cmp_gt_u32 s61, 14
	s_cbranch_scc0 .LBB0_945

.LBB0_950:
	v_lshlrev_b32_e32 v0, 1, v135
	v_lshlrev_b32_e32 v1, 1, v154
	v_add3_u32 v2, s62, v0, v1
	v_add_u32_e32 v207, s62, v63
	v_lshl_add_u32 v227, v54, 1, v207
	v_add_u32_e32 v0, v2, v176
	ds_read_b128 v[36:39], v2 offset:4352
	ds_read_b128 v[40:43], v2
	ds_read_b128 v[208:211], v2 offset:4416
	ds_read_b128 v[184:187], v2 offset:64
	ds_read_b128 v[212:215], v2 offset:4480
	ds_read_b128 v[228:231], v2 offset:128
	ds_read_b128 v[232:235], v2 offset:4544
	ds_read_b128 v[236:239], v2 offset:192
	ds_read_b64 v[188:189], v227 offset:14848
	ds_read2_b64 v[240:243], v0 offset1:4
	ds_read2_b64 v[244:247], v0 offset0:8 offset1:12
	s_and_b64 s[12:13], s[54:55], s[52:53]
	v_mov_b32_e32 v190, v3
	v_mov_b32_e32 v191, v3
	s_waitcnt lgkmcnt(9)
	v_mfma_f32_16x16x32_bf16 v[36:39], v[36:39], v[40:43], 0
	s_waitcnt lgkmcnt(7)
	v_mfma_f32_16x16x32_bf16 v[36:39], v[208:211], v[184:187], v[36:39]
	s_waitcnt lgkmcnt(5)
	v_mfma_f32_16x16x32_bf16 v[36:39], v[212:215], v[228:231], v[36:39]
	s_waitcnt lgkmcnt(3)
	v_mfma_f32_16x16x32_bf16 v[36:39], v[232:235], v[236:239], v[36:39]
	ds_read2_b64 v[208:211], v0 offset0:16 offset1:20
	ds_read2_b64 v[212:215], v0 offset0:24 offset1:28
	v_cvt_pk_bf16_f32 v184, v4, v5
	v_cvt_pk_bf16_f32 v185, v6, v7
	v_cvt_pk_bf16_f32 v186, v8, v9
	v_cvt_pk_bf16_f32 v187, v10, v11
	v_mov_b32_e32 v2, v3
	s_nop 0
	v_cndmask_b32_e64 v192, v38, 0, s[12:13]
	s_and_b64 s[12:13], s[12:13], s[50:51]
	v_cndmask_b32_e64 v0, v37, 0, s[12:13]
	s_and_b64 s[12:13], s[12:13], s[48:49]
	v_cndmask_b32_e64 v36, v36, 0, s[12:13]
	v_cndmask_b32_e64 v1, v39, 0, s[54:55]
	v_cvt_pk_bf16_f32 v0, v36, v0
	v_cvt_pk_bf16_f32 v1, v192, v1
	s_nop 0
	s_waitcnt lgkmcnt(4)
	v_mfma_f32_16x16x32_bf16 v[36:39], v[188:191], v[0:3], 0
	v_cvt_pk_bf16_f32 v40, v12, v13
	v_cvt_pk_bf16_f32 v41, v14, v15
	v_cvt_pk_bf16_f32 v42, v16, v17
	v_cvt_pk_bf16_f32 v43, v18, v19
	v_cvt_pk_bf16_f32 v228, v20, v21
	v_cvt_pk_bf16_f32 v229, v22, v23
	v_cvt_pk_bf16_f32 v230, v24, v25
	v_cvt_pk_bf16_f32 v231, v26, v27
	v_cvt_pk_bf16_f32 v232, v28, v29
	v_cvt_pk_bf16_f32 v233, v30, v31
	v_cvt_pk_bf16_f32 v234, v32, v33
	v_cvt_pk_bf16_f32 v235, v34, v35
	s_waitcnt lgkmcnt(3)
	v_mfma_f32_16x16x32_bf16 v[36:39], v[184:187], v[240:243], v[36:39]
	s_waitcnt lgkmcnt(2)
	v_mfma_f32_16x16x32_bf16 v[36:39], v[40:43], v[244:247], v[36:39]
	s_waitcnt lgkmcnt(1)
	v_mfma_f32_16x16x32_bf16 v[36:39], v[228:231], v[208:211], v[36:39]
	s_waitcnt lgkmcnt(0)
	v_mfma_f32_16x16x32_bf16 v[36:39], v[232:235], v[212:215], v[36:39]
	v_add_u32_e32 v227, v207, v155
	v_lshl_add_u32 v216, v54, 2, s62
	v_add3_u32 v217, s62, v155, v156
	v_mov_b32_e32 v32, 0
	v_mov_b32_e32 v33, 0
	v_mov_b32_e32 v34, 0
	v_mov_b32_e32 v35, 0
	s_and_saveexec_b64 s[12:13], s[46:47]
	ds_read_b128 v[32:35], v227 offset:14848
	s_or_b64 exec, exec, s[12:13]
	ds_read_b128 v[240:243], v216 offset:20992
	ds_read_b128 v[184:187], v217 offset:8704
	ds_read_b128 v[244:247], v216 offset:21056
	ds_read_b128 v[40:43], v217 offset:9472
	ds_read_b128 v[208:211], v216 offset:21120
	ds_read_b128 v[228:231], v217 offset:10240
	ds_read_b128 v[212:215], v216 offset:21184
	ds_read_b128 v[232:235], v217 offset:11008
	s_ashr_i32 s12, s32, 4
	s_add_i32 s12, s12, -2
	v_sub_u32_e32 v0, v51, v54
	v_cvt_pk_bf16_f32 v192, v36, v37
	v_cvt_pk_bf16_f32 v193, v38, v39
	v_mad_i32_i24 v0, v0, s12, v197
	global_store_dwordx2 v0, v[192:193], s[100:101]
	s_waitcnt lgkmcnt(6)
	v_pk_mul_f32 v[6:7], v[6:7], v[242:243]
	v_pk_mul_f32 v[4:5], v[4:5], v[240:241]
	s_nop 1
	v_mfma_f32_16x16x32_bf16 v[4:7], v[184:187], v[32:35], v[4:7]
	ds_read_b128 v[240:243], v216 offset:21248
	ds_read_b128 v[184:187], v217 offset:11776
	s_waitcnt lgkmcnt(6)
	v_pk_mul_f32 v[10:11], v[10:11], v[246:247]
	v_pk_mul_f32 v[8:9], v[8:9], v[244:245]
	s_nop 1
	v_mfma_f32_16x16x32_bf16 v[8:11], v[40:43], v[32:35], v[8:11]
	ds_read_b128 v[244:247], v216 offset:21312
	ds_read_b128 v[40:43], v217 offset:12544
	s_waitcnt lgkmcnt(6)
	v_pk_mul_f32 v[14:15], v[14:15], v[210:211]
	v_pk_mul_f32 v[12:13], v[12:13], v[208:209]
	s_nop 1
	v_mfma_f32_16x16x32_bf16 v[12:15], v[228:231], v[32:35], v[12:15]
	ds_read_b128 v[208:211], v216 offset:21376
	ds_read_b128 v[228:231], v217 offset:13312
	s_waitcnt lgkmcnt(6)
	v_pk_mul_f32 v[18:19], v[18:19], v[214:215]
	v_pk_mul_f32 v[16:17], v[16:17], v[212:213]
	s_nop 1
	v_mfma_f32_16x16x32_bf16 v[16:19], v[232:235], v[32:35], v[16:19]
	ds_read_b128 v[212:215], v216 offset:21440
	ds_read_b128 v[232:235], v217 offset:14080
	s_waitcnt lgkmcnt(6)
	v_pk_mul_f32 v[22:23], v[22:23], v[242:243]
	v_pk_mul_f32 v[20:21], v[20:21], v[240:241]
	s_nop 1
	v_mfma_f32_16x16x32_bf16 v[20:23], v[184:187], v[32:35], v[20:23]
	s_waitcnt lgkmcnt(4)
	v_pk_mul_f32 v[26:27], v[26:27], v[246:247]
	v_pk_mul_f32 v[24:25], v[24:25], v[244:245]
	s_nop 1
	v_mfma_f32_16x16x32_bf16 v[24:27], v[40:43], v[32:35], v[24:27]
	s_waitcnt lgkmcnt(2)
	v_pk_mul_f32 v[30:31], v[30:31], v[210:211]
	v_pk_mul_f32 v[28:29], v[28:29], v[208:209]
	s_nop 1
	v_mfma_f32_16x16x32_bf16 v[28:31], v[228:231], v[32:35], v[28:31]
	s_waitcnt lgkmcnt(0)
	v_pk_mul_f32 v[214:215], v[150:151], v[214:215]
	v_pk_mul_f32 v[212:213], v[148:149], v[212:213]
	s_nop 1
	v_mfma_f32_16x16x32_bf16 v[32:35], v[232:235], v[32:35], v[212:215]
	v_add_u32_e32 v197, s32, v197
	v_add_u32_e32 v198, s32, v198
	v_add_u32_e32 v248, s32, v248
	v_add_u32_e32 v249, s32, v249
	v_lshl_add_u64 v[48:49], v[48:49], 0, v[46:47]
	s_add_i32 s60, s60, 16
	s_add_i32 s61, s61, 1
	s_cmpk_lg_i32 s60, 0x100
	s_barrier
	s_cbranch_scc1 .LBB0_943
	s_mov_b64 s[58:59], -1
	s_branch .LBB0_1005
.Lhc_alt_top:
	s_nop 2
	v_mov_b32_e32 v148, v32
	v_mov_b32_e32 v149, v33
	v_mov_b32_e32 v150, v34
	v_mov_b32_e32 v151, v35
	s_bitcmp1_b32 s61, 0
	s_cselect_b32 s62, 0x5800, 0
	v_lshlrev_b32_e32 v0, 1, v135
	v_lshlrev_b32_e32 v1, 1, v154
	v_add3_u32 v2, s62, v0, v1
	v_add_u32_e32 v207, s62, v63
	v_lshl_add_u32 v227, v54, 1, v207
	v_add_u32_e32 v0, v2, v176
	ds_read_b128 v[36:39], v2 offset:4352
	ds_read_b128 v[40:43], v2
	ds_read_b128 v[208:211], v2 offset:4416
	ds_read_b128 v[184:187], v2 offset:64
	ds_read_b128 v[212:215], v2 offset:4480
	ds_read_b128 v[228:231], v2 offset:128
	ds_read_b128 v[232:235], v2 offset:4544
	ds_read_b128 v[236:239], v2 offset:192
	ds_read_b64 v[188:189], v227 offset:14848
	ds_read2_b64 v[240:243], v0 offset1:4
	ds_read2_b64 v[244:247], v0 offset0:8 offset1:12
	s_and_b64 s[12:13], s[54:55], s[52:53]
	v_mov_b32_e32 v190, v3
	v_mov_b32_e32 v191, v3
	s_waitcnt lgkmcnt(9)
	v_mfma_f32_16x16x32_bf16 v[36:39], v[36:39], v[40:43], 0
	s_waitcnt lgkmcnt(7)
	v_mfma_f32_16x16x32_bf16 v[36:39], v[208:211], v[184:187], v[36:39]
	s_waitcnt lgkmcnt(5)
	v_mfma_f32_16x16x32_bf16 v[36:39], v[212:215], v[228:231], v[36:39]
	s_waitcnt lgkmcnt(3)
	v_mfma_f32_16x16x32_bf16 v[36:39], v[232:235], v[236:239], v[36:39]
	ds_read2_b64 v[208:211], v0 offset0:16 offset1:20
	ds_read2_b64 v[212:215], v0 offset0:24 offset1:28
	v_cvt_pk_bf16_f32 v184, v4, v5
	v_cvt_pk_bf16_f32 v185, v6, v7
	v_cvt_pk_bf16_f32 v186, v8, v9
	v_cvt_pk_bf16_f32 v187, v10, v11
	v_mov_b32_e32 v2, v3
	s_nop 0
	v_cndmask_b32_e64 v192, v38, 0, s[12:13]
	s_and_b64 s[12:13], s[12:13], s[50:51]
	v_cndmask_b32_e64 v0, v37, 0, s[12:13]
	s_and_b64 s[12:13], s[12:13], s[48:49]
	v_cndmask_b32_e64 v36, v36, 0, s[12:13]
	v_cndmask_b32_e64 v1, v39, 0, s[54:55]
	v_cvt_pk_bf16_f32 v0, v36, v0
	v_cvt_pk_bf16_f32 v1, v192, v1
	s_nop 0
	s_waitcnt lgkmcnt(4)
	v_mfma_f32_16x16x32_bf16 v[36:39], v[188:191], v[0:3], 0
	v_cvt_pk_bf16_f32 v40, v12, v13
	v_cvt_pk_bf16_f32 v41, v14, v15
	v_cvt_pk_bf16_f32 v42, v16, v17
	v_cvt_pk_bf16_f32 v43, v18, v19
	v_cvt_pk_bf16_f32 v228, v20, v21
	v_cvt_pk_bf16_f32 v229, v22, v23
	v_cvt_pk_bf16_f32 v230, v24, v25
	v_cvt_pk_bf16_f32 v231, v26, v27
	v_cvt_pk_bf16_f32 v232, v28, v29
	v_cvt_pk_bf16_f32 v233, v30, v31
	v_cvt_pk_bf16_f32 v234, v32, v33
	v_cvt_pk_bf16_f32 v235, v34, v35
	s_waitcnt lgkmcnt(3)
	v_mfma_f32_16x16x32_bf16 v[36:39], v[184:187], v[240:243], v[36:39]
	s_waitcnt lgkmcnt(2)
	v_mfma_f32_16x16x32_bf16 v[36:39], v[40:43], v[244:247], v[36:39]
	s_waitcnt lgkmcnt(1)
	v_mfma_f32_16x16x32_bf16 v[36:39], v[228:231], v[208:211], v[36:39]
	s_waitcnt lgkmcnt(0)
	v_mfma_f32_16x16x32_bf16 v[36:39], v[232:235], v[212:215], v[36:39]
	v_add_u32_e32 v227, v207, v155
	v_lshl_add_u32 v216, v54, 2, s62
	v_add3_u32 v217, s62, v155, v156
	v_mov_b32_e32 v32, 0
	v_mov_b32_e32 v33, 0
	v_mov_b32_e32 v34, 0
	v_mov_b32_e32 v35, 0
	s_and_saveexec_b64 s[12:13], s[46:47]
	ds_read_b128 v[32:35], v227 offset:14848
	s_or_b64 exec, exec, s[12:13]
	ds_read_b128 v[240:243], v216 offset:20992
	ds_read_b128 v[184:187], v217 offset:8704
	ds_read_b128 v[244:247], v216 offset:21056
	ds_read_b128 v[40:43], v217 offset:9472
	ds_read_b128 v[208:211], v216 offset:21120
	ds_read_b128 v[228:231], v217 offset:10240
	ds_read_b128 v[212:215], v216 offset:21184
	ds_read_b128 v[232:235], v217 offset:11008
	s_ashr_i32 s12, s32, 4
	s_add_i32 s12, s12, -2
	v_sub_u32_e32 v0, v51, v54
	v_cvt_pk_bf16_f32 v192, v36, v37
	v_cvt_pk_bf16_f32 v193, v38, v39
	v_mad_i32_i24 v0, v0, s12, v197
	global_store_dwordx2 v0, v[192:193], s[100:101]
	s_waitcnt lgkmcnt(6)
	v_pk_mul_f32 v[6:7], v[6:7], v[242:243]
	v_pk_mul_f32 v[4:5], v[4:5], v[240:241]
	s_nop 1
	v_mfma_f32_16x16x32_bf16 v[4:7], v[184:187], v[32:35], v[4:7]
	ds_read_b128 v[240:243], v216 offset:21248
	ds_read_b128 v[184:187], v217 offset:11776
	s_waitcnt lgkmcnt(6)
	v_pk_mul_f32 v[10:11], v[10:11], v[246:247]
	v_pk_mul_f32 v[8:9], v[8:9], v[244:245]
	s_nop 1
	v_mfma_f32_16x16x32_bf16 v[8:11], v[40:43], v[32:35], v[8:11]
	ds_read_b128 v[244:247], v216 offset:21312
	ds_read_b128 v[40:43], v217 offset:12544
	s_waitcnt lgkmcnt(6)
	v_pk_mul_f32 v[14:15], v[14:15], v[210:211]
	v_pk_mul_f32 v[12:13], v[12:13], v[208:209]
	s_nop 1
	v_mfma_f32_16x16x32_bf16 v[12:15], v[228:231], v[32:35], v[12:15]
	ds_read_b128 v[208:211], v216 offset:21376
	ds_read_b128 v[228:231], v217 offset:13312
	s_waitcnt lgkmcnt(6)
	v_pk_mul_f32 v[18:19], v[18:19], v[214:215]
	v_pk_mul_f32 v[16:17], v[16:17], v[212:213]
	s_nop 1
	v_mfma_f32_16x16x32_bf16 v[16:19], v[232:235], v[32:35], v[16:19]
	ds_read_b128 v[212:215], v216 offset:21440
	ds_read_b128 v[232:235], v217 offset:14080
	s_waitcnt lgkmcnt(6)
	v_pk_mul_f32 v[22:23], v[22:23], v[242:243]
	v_pk_mul_f32 v[20:21], v[20:21], v[240:241]
	s_nop 1
	v_mfma_f32_16x16x32_bf16 v[20:23], v[184:187], v[32:35], v[20:23]
	s_waitcnt lgkmcnt(4)
	v_pk_mul_f32 v[26:27], v[26:27], v[246:247]
	v_pk_mul_f32 v[24:25], v[24:25], v[244:245]
	s_nop 1
	v_mfma_f32_16x16x32_bf16 v[24:27], v[40:43], v[32:35], v[24:27]
	s_waitcnt lgkmcnt(2)
	v_pk_mul_f32 v[30:31], v[30:31], v[210:211]
	v_pk_mul_f32 v[28:29], v[28:29], v[208:209]
	s_nop 1
	v_mfma_f32_16x16x32_bf16 v[28:31], v[228:231], v[32:35], v[28:31]
	s_waitcnt lgkmcnt(0)
	v_pk_mul_f32 v[214:215], v[150:151], v[214:215]
	v_pk_mul_f32 v[212:213], v[148:149], v[212:213]
	s_nop 1
	v_mfma_f32_16x16x32_bf16 v[32:35], v[232:235], v[32:35], v[212:215]
	s_cmp_gt_u32 s61, 14
	s_cbranch_scc1 .Lhc_alt_tail
	s_waitcnt vmcnt(1)
	v_mov_b32_e32 v44, v200
	v_mov_b32_e32 v42, v202
	v_mov_b32_e32 v40, v204
	v_mov_b32_e32 v38, v206
	v_mov_b32_e32 v45, v199
	v_mov_b32_e32 v43, v201
	v_mov_b32_e32 v41, v203
	v_mov_b32_e32 v39, v205
	v_mov_b64_e32 v[36:37], v[152:153]
	s_cmpk_eq_i32 s60, 0xe0
	s_cbranch_scc1 .Lhc_alt_947
	global_load_ushort v199, v197, s[24:25]
	global_load_ushort v200, v197, s[98:99]
	global_load_ushort v201, v198, s[24:25]
	global_load_ushort v202, v198, s[98:99]
	global_load_ushort v203, v248, s[24:25]
	global_load_ushort v204, v248, s[98:99]
	global_load_ushort v205, v249, s[24:25]
	global_load_ushort v206, v249, s[98:99]
	global_load_dwordx2 v[152:153], v[48:49], off

.LBB0_979:
	s_bitcmp1_b32 s81, 0
	s_cselect_b32 s82, 0x5800, 0
	s_add_i32 s14, s81, -1
	s_cmp_ge_u32 s14, s61
	s_cbranch_scc1 .LBB0_985
	s_cmp_ge_u32 s81, s61
	s_waitcnt vmcnt(1)
	v_mov_b32_e32 v199, v157
	v_mov_b32_e32 v200, v159
	v_mov_b32_e32 v201, v161
	v_mov_b32_e32 v202, v163
	v_mov_b32_e32 v203, v166
	v_mov_b32_e32 v204, v167
	v_mov_b32_e32 v205, v168
	v_mov_b32_e32 v206, v169
	v_mov_b64_e32 v[148:149], v[164:165]
	s_cbranch_scc1 .LBB0_982
	global_load_ushort v168, v197, s[12:13]
	global_load_ushort v169, v197, s[98:99]
	global_load_ushort v166, v198, s[12:13]
	global_load_ushort v167, v198, s[98:99]
	global_load_ushort v161, v178, s[12:13]
	global_load_ushort v163, v178, s[98:99]
	global_load_ushort v157, v179, s[12:13]
	global_load_ushort v159, v179, s[98:99]
	global_load_dwordx2 v[164:165], v[150:151], off

.LBB0_985:
	v_lshlrev_b32_e32 v0, 1, v135
	v_lshlrev_b32_e32 v1, 1, v154
	v_add3_u32 v2, s82, v0, v1
	v_add_u32_e32 v207, s82, v63
	v_lshl_add_u32 v227, v54, 1, v207
	v_add_u32_e32 v0, v2, v176
	ds_read_b128 v[36:39], v2 offset:4352
	ds_read_b128 v[40:43], v2
	ds_read_b128 v[208:211], v2 offset:4416
	ds_read_b128 v[184:187], v2 offset:64
	ds_read_b128 v[212:215], v2 offset:4480
	ds_read_b128 v[228:231], v2 offset:128
	ds_read_b128 v[232:235], v2 offset:4544
	ds_read_b128 v[236:239], v2 offset:192
	ds_read_b64 v[188:189], v227 offset:14848
	ds_read2_b64 v[240:243], v0 offset1:4
	ds_read2_b64 v[244:247], v0 offset0:8 offset1:12
	s_and_b64 s[14:15], s[54:55], s[52:53]
	v_mov_b32_e32 v190, v3
	v_mov_b32_e32 v191, v3
	s_waitcnt lgkmcnt(9)
	v_mfma_f32_16x16x32_bf16 v[36:39], v[36:39], v[40:43], 0
	s_waitcnt lgkmcnt(7)
	v_mfma_f32_16x16x32_bf16 v[36:39], v[208:211], v[184:187], v[36:39]
	s_waitcnt lgkmcnt(5)
	v_mfma_f32_16x16x32_bf16 v[36:39], v[212:215], v[228:231], v[36:39]
	s_waitcnt lgkmcnt(3)
	v_mfma_f32_16x16x32_bf16 v[36:39], v[232:235], v[236:239], v[36:39]
	ds_read2_b64 v[208:211], v0 offset0:16 offset1:20
	ds_read2_b64 v[212:215], v0 offset0:24 offset1:28
	v_cvt_pk_bf16_f32 v184, v4, v5
	v_cvt_pk_bf16_f32 v185, v6, v7
	v_cvt_pk_bf16_f32 v186, v8, v9
	v_cvt_pk_bf16_f32 v187, v10, v11
	v_mov_b32_e32 v2, v3
	s_nop 0
	v_cndmask_b32_e64 v192, v38, 0, s[14:15]
	s_and_b64 s[14:15], s[14:15], s[50:51]
	v_cndmask_b32_e64 v0, v37, 0, s[14:15]
	s_and_b64 s[14:15], s[14:15], s[48:49]
	v_cndmask_b32_e64 v36, v36, 0, s[14:15]
	v_cndmask_b32_e64 v1, v39, 0, s[54:55]
	v_cvt_pk_bf16_f32 v0, v36, v0
	v_cvt_pk_bf16_f32 v1, v192, v1
	s_nop 0
	s_waitcnt lgkmcnt(4)
	v_mfma_f32_16x16x32_bf16 v[36:39], v[188:191], v[0:3], 0
	v_cvt_pk_bf16_f32 v40, v12, v13
	v_cvt_pk_bf16_f32 v41, v14, v15
	v_cvt_pk_bf16_f32 v42, v16, v17
	v_cvt_pk_bf16_f32 v43, v18, v19
	v_cvt_pk_bf16_f32 v228, v20, v21
	v_cvt_pk_bf16_f32 v229, v22, v23
	v_cvt_pk_bf16_f32 v230, v24, v25
	v_cvt_pk_bf16_f32 v231, v26, v27
	v_cvt_pk_bf16_f32 v232, v28, v29
	v_cvt_pk_bf16_f32 v233, v30, v31
	v_cvt_pk_bf16_f32 v234, v32, v33
	v_cvt_pk_bf16_f32 v235, v34, v35
	s_waitcnt lgkmcnt(3)
	v_mfma_f32_16x16x32_bf16 v[36:39], v[184:187], v[240:243], v[36:39]
	s_waitcnt lgkmcnt(2)
	v_mfma_f32_16x16x32_bf16 v[36:39], v[40:43], v[244:247], v[36:39]
	s_waitcnt lgkmcnt(1)
	v_mfma_f32_16x16x32_bf16 v[36:39], v[228:231], v[208:211], v[36:39]
	s_waitcnt lgkmcnt(0)
	v_mfma_f32_16x16x32_bf16 v[36:39], v[232:235], v[212:215], v[36:39]
	v_add_u32_e32 v227, v207, v155
	v_lshl_add_u32 v216, v54, 2, s82
	v_add3_u32 v217, s82, v155, v156
	v_mov_b32_e32 v44, 0
	v_mov_b32_e32 v45, 0
	v_mov_b32_e32 v46, 0
	v_mov_b32_e32 v47, 0
	s_and_saveexec_b64 s[14:15], s[46:47]
	ds_read_b128 v[44:47], v227 offset:14848
	s_or_b64 exec, exec, s[14:15]
	ds_read_b128 v[240:243], v216 offset:20992
	ds_read_b128 v[184:187], v217 offset:8704
	ds_read_b128 v[244:247], v216 offset:21056
	ds_read_b128 v[40:43], v217 offset:9472
	ds_read_b128 v[208:211], v216 offset:21120
	ds_read_b128 v[228:231], v217 offset:10240
	ds_read_b128 v[212:215], v216 offset:21184
	ds_read_b128 v[232:235], v217 offset:11008
	s_ashr_i32 s14, s32, 4
	s_add_i32 s14, s14, -2
	v_sub_u32_e32 v0, v51, v54
	v_cvt_pk_bf16_f32 v192, v36, v37
	v_cvt_pk_bf16_f32 v193, v38, v39
	v_mad_i32_i24 v0, v0, s14, v197
	global_store_dwordx2 v0, v[192:193], s[100:101]
	s_waitcnt lgkmcnt(6)
	v_pk_mul_f32 v[6:7], v[6:7], v[242:243]
	v_pk_mul_f32 v[4:5], v[4:5], v[240:241]
	s_nop 1
	v_mfma_f32_16x16x32_bf16 v[4:7], v[184:187], v[44:47], v[4:7]
	ds_read_b128 v[240:243], v216 offset:21248
	ds_read_b128 v[184:187], v217 offset:11776
	s_waitcnt lgkmcnt(6)
	v_pk_mul_f32 v[10:11], v[10:11], v[246:247]
	v_pk_mul_f32 v[8:9], v[8:9], v[244:245]
	s_nop 1
	v_mfma_f32_16x16x32_bf16 v[8:11], v[40:43], v[44:47], v[8:11]
	ds_read_b128 v[244:247], v216 offset:21312
	ds_read_b128 v[40:43], v217 offset:12544
	s_waitcnt lgkmcnt(6)
	v_pk_mul_f32 v[14:15], v[14:15], v[210:211]
	v_pk_mul_f32 v[12:13], v[12:13], v[208:209]
	s_nop 1
	v_mfma_f32_16x16x32_bf16 v[12:15], v[228:231], v[44:47], v[12:15]
	ds_read_b128 v[208:211], v216 offset:21376
	ds_read_b128 v[228:231], v217 offset:13312
	s_waitcnt lgkmcnt(6)
	v_pk_mul_f32 v[18:19], v[18:19], v[214:215]
	v_pk_mul_f32 v[16:17], v[16:17], v[212:213]
	s_nop 1
	v_mfma_f32_16x16x32_bf16 v[16:19], v[232:235], v[44:47], v[16:19]
	ds_read_b128 v[212:215], v216 offset:21440
	ds_read_b128 v[232:235], v217 offset:14080
	s_waitcnt lgkmcnt(6)
	v_pk_mul_f32 v[22:23], v[22:23], v[242:243]
	v_pk_mul_f32 v[20:21], v[20:21], v[240:241]
	s_nop 1
	v_mfma_f32_16x16x32_bf16 v[20:23], v[184:187], v[44:47], v[20:23]
	s_waitcnt lgkmcnt(4)
	v_pk_mul_f32 v[26:27], v[26:27], v[246:247]
	v_pk_mul_f32 v[24:25], v[24:25], v[244:245]
	s_nop 1
	v_mfma_f32_16x16x32_bf16 v[24:27], v[40:43], v[44:47], v[24:27]
	s_waitcnt lgkmcnt(2)
	v_pk_mul_f32 v[30:31], v[30:31], v[210:211]
	v_pk_mul_f32 v[28:29], v[28:29], v[208:209]
	s_nop 1
	v_mfma_f32_16x16x32_bf16 v[28:31], v[228:231], v[44:47], v[28:31]
	s_waitcnt lgkmcnt(0)
	v_pk_mul_f32 v[34:35], v[34:35], v[214:215]
	v_pk_mul_f32 v[32:33], v[32:33], v[212:213]
	s_nop 1
	v_mfma_f32_16x16x32_bf16 v[32:35], v[232:235], v[44:47], v[32:35]
	v_add_u32_e32 v197, s32, v197
	v_add_u32_e32 v198, s32, v198
	v_add_u32_e32 v178, s32, v178
	v_add_u32_e32 v179, s32, v179
	v_lshl_add_u64 v[150:151], v[150:151], 0, v[146:147]
	s_add_i32 s81, s81, 1
	s_add_i32 s62, s62, 16
	s_add_i32 s14, s80, s81
	s_cmp_eq_u32 s14, 2
	s_barrier
	s_cbranch_scc1 .LBB0_1003
	s_branch .LBB0_979
.Lhl_alt_top:
	s_bitcmp1_b32 s81, 0
	s_cselect_b32 s82, 0x5800, 0
	v_lshlrev_b32_e32 v0, 1, v135
	v_lshlrev_b32_e32 v1, 1, v154
	v_add3_u32 v2, s82, v0, v1
	v_add_u32_e32 v207, s82, v63
	v_lshl_add_u32 v227, v54, 1, v207
	v_add_u32_e32 v0, v2, v176
	ds_read_b128 v[36:39], v2 offset:4352
	ds_read_b128 v[40:43], v2
	ds_read_b128 v[208:211], v2 offset:4416
	ds_read_b128 v[184:187], v2 offset:64
	ds_read_b128 v[212:215], v2 offset:4480
	ds_read_b128 v[228:231], v2 offset:128
	ds_read_b128 v[232:235], v2 offset:4544
	ds_read_b128 v[236:239], v2 offset:192
	ds_read_b64 v[188:189], v227 offset:14848
	ds_read2_b64 v[240:243], v0 offset1:4
	ds_read2_b64 v[244:247], v0 offset0:8 offset1:12
	s_and_b64 s[14:15], s[54:55], s[52:53]
	v_mov_b32_e32 v190, v3
	v_mov_b32_e32 v191, v3
	s_waitcnt lgkmcnt(9)
	v_mfma_f32_16x16x32_bf16 v[36:39], v[36:39], v[40:43], 0
	s_waitcnt lgkmcnt(7)
	v_mfma_f32_16x16x32_bf16 v[36:39], v[208:211], v[184:187], v[36:39]
	s_waitcnt lgkmcnt(5)
	v_mfma_f32_16x16x32_bf16 v[36:39], v[212:215], v[228:231], v[36:39]
	s_waitcnt lgkmcnt(3)
	v_mfma_f32_16x16x32_bf16 v[36:39], v[232:235], v[236:239], v[36:39]
	ds_read2_b64 v[208:211], v0 offset0:16 offset1:20
	ds_read2_b64 v[212:215], v0 offset0:24 offset1:28
	v_cvt_pk_bf16_f32 v184, v4, v5
	v_cvt_pk_bf16_f32 v185, v6, v7
	v_cvt_pk_bf16_f32 v186, v8, v9
	v_cvt_pk_bf16_f32 v187, v10, v11
	v_mov_b32_e32 v2, v3
	s_nop 0
	v_cndmask_b32_e64 v192, v38, 0, s[14:15]
	s_and_b64 s[14:15], s[14:15], s[50:51]
	v_cndmask_b32_e64 v0, v37, 0, s[14:15]
	s_and_b64 s[14:15], s[14:15], s[48:49]
	v_cndmask_b32_e64 v36, v36, 0, s[14:15]
	v_cndmask_b32_e64 v1, v39, 0, s[54:55]
	v_cvt_pk_bf16_f32 v0, v36, v0
	v_cvt_pk_bf16_f32 v1, v192, v1
	s_nop 0
	s_waitcnt lgkmcnt(4)
	v_mfma_f32_16x16x32_bf16 v[36:39], v[188:191], v[0:3], 0
	v_cvt_pk_bf16_f32 v40, v12, v13
	v_cvt_pk_bf16_f32 v41, v14, v15
	v_cvt_pk_bf16_f32 v42, v16, v17
	v_cvt_pk_bf16_f32 v43, v18, v19
	v_cvt_pk_bf16_f32 v228, v20, v21
	v_cvt_pk_bf16_f32 v229, v22, v23
	v_cvt_pk_bf16_f32 v230, v24, v25
	v_cvt_pk_bf16_f32 v231, v26, v27
	v_cvt_pk_bf16_f32 v232, v28, v29
	v_cvt_pk_bf16_f32 v233, v30, v31
	v_cvt_pk_bf16_f32 v234, v32, v33
	v_cvt_pk_bf16_f32 v235, v34, v35
	s_waitcnt lgkmcnt(3)
	v_mfma_f32_16x16x32_bf16 v[36:39], v[184:187], v[240:243], v[36:39]
	s_waitcnt lgkmcnt(2)
	v_mfma_f32_16x16x32_bf16 v[36:39], v[40:43], v[244:247], v[36:39]
	s_waitcnt lgkmcnt(1)
	v_mfma_f32_16x16x32_bf16 v[36:39], v[228:231], v[208:211], v[36:39]
	s_waitcnt lgkmcnt(0)
	v_mfma_f32_16x16x32_bf16 v[36:39], v[232:235], v[212:215], v[36:39]
	v_add_u32_e32 v227, v207, v155
	v_lshl_add_u32 v216, v54, 2, s82
	v_add3_u32 v217, s82, v155, v156
	v_mov_b32_e32 v44, 0
	v_mov_b32_e32 v45, 0
	v_mov_b32_e32 v46, 0
	v_mov_b32_e32 v47, 0
	s_and_saveexec_b64 s[14:15], s[46:47]
	ds_read_b128 v[44:47], v227 offset:14848
	s_or_b64 exec, exec, s[14:15]
	ds_read_b128 v[240:243], v216 offset:20992
	ds_read_b128 v[184:187], v217 offset:8704
	ds_read_b128 v[244:247], v216 offset:21056
	ds_read_b128 v[40:43], v217 offset:9472
	ds_read_b128 v[208:211], v216 offset:21120
	ds_read_b128 v[228:231], v217 offset:10240
	ds_read_b128 v[212:215], v216 offset:21184
	ds_read_b128 v[232:235], v217 offset:11008
	s_ashr_i32 s14, s32, 4
	s_add_i32 s14, s14, -2
	v_sub_u32_e32 v0, v51, v54
	v_cvt_pk_bf16_f32 v192, v36, v37
	v_cvt_pk_bf16_f32 v193, v38, v39
	v_mad_i32_i24 v0, v0, s14, v197
	global_store_dwordx2 v0, v[192:193], s[100:101]
	s_waitcnt lgkmcnt(6)
	v_pk_mul_f32 v[6:7], v[6:7], v[242:243]
	v_pk_mul_f32 v[4:5], v[4:5], v[240:241]
	s_nop 1
	v_mfma_f32_16x16x32_bf16 v[4:7], v[184:187], v[44:47], v[4:7]
	ds_read_b128 v[240:243], v216 offset:21248
	ds_read_b128 v[184:187], v217 offset:11776
	s_waitcnt lgkmcnt(6)
	v_pk_mul_f32 v[10:11], v[10:11], v[246:247]
	v_pk_mul_f32 v[8:9], v[8:9], v[244:245]
	s_nop 1
	v_mfma_f32_16x16x32_bf16 v[8:11], v[40:43], v[44:47], v[8:11]
	ds_read_b128 v[244:247], v216 offset:21312
	ds_read_b128 v[40:43], v217 offset:12544
	s_waitcnt lgkmcnt(6)
	v_pk_mul_f32 v[14:15], v[14:15], v[210:211]
	v_pk_mul_f32 v[12:13], v[12:13], v[208:209]
	s_nop 1
	v_mfma_f32_16x16x32_bf16 v[12:15], v[228:231], v[44:47], v[12:15]
	ds_read_b128 v[208:211], v216 offset:21376
	ds_read_b128 v[228:231], v217 offset:13312
	s_waitcnt lgkmcnt(6)
	v_pk_mul_f32 v[18:19], v[18:19], v[214:215]
	v_pk_mul_f32 v[16:17], v[16:17], v[212:213]
	s_nop 1
	v_mfma_f32_16x16x32_bf16 v[16:19], v[232:235], v[44:47], v[16:19]
	ds_read_b128 v[212:215], v216 offset:21440
	ds_read_b128 v[232:235], v217 offset:14080
	s_waitcnt lgkmcnt(6)
	v_pk_mul_f32 v[22:23], v[22:23], v[242:243]
	v_pk_mul_f32 v[20:21], v[20:21], v[240:241]
	s_nop 1
	v_mfma_f32_16x16x32_bf16 v[20:23], v[184:187], v[44:47], v[20:23]
	s_waitcnt lgkmcnt(4)
	v_pk_mul_f32 v[26:27], v[26:27], v[246:247]
	v_pk_mul_f32 v[24:25], v[24:25], v[244:245]
	s_nop 1
	v_mfma_f32_16x16x32_bf16 v[24:27], v[40:43], v[44:47], v[24:27]
	s_waitcnt lgkmcnt(2)
	v_pk_mul_f32 v[30:31], v[30:31], v[210:211]
	v_pk_mul_f32 v[28:29], v[28:29], v[208:209]
	s_nop 1
	v_mfma_f32_16x16x32_bf16 v[28:31], v[228:231], v[44:47], v[28:31]
	s_waitcnt lgkmcnt(0)
	v_pk_mul_f32 v[34:35], v[34:35], v[214:215]
	v_pk_mul_f32 v[32:33], v[32:33], v[212:213]
	s_nop 1
	v_mfma_f32_16x16x32_bf16 v[32:35], v[232:235], v[44:47], v[32:35]
	s_add_i32 s14, s81, -1
	s_cmp_ge_u32 s14, s61
	s_cbranch_scc1 .Lhl_alt_tail
	s_cmp_ge_u32 s81, s61
	s_waitcnt vmcnt(1)
	v_mov_b32_e32 v199, v157
	v_mov_b32_e32 v200, v159
	v_mov_b32_e32 v201, v161
	v_mov_b32_e32 v202, v163
	v_mov_b32_e32 v203, v166
	v_mov_b32_e32 v204, v167
	v_mov_b32_e32 v205, v168
	v_mov_b32_e32 v206, v169
	v_mov_b64_e32 v[148:149], v[164:165]
	s_cbranch_scc1 .Lhl_alt_982
	global_load_ushort v168, v197, s[12:13]
	global_load_ushort v169, v197, s[98:99]
	global_load_ushort v166, v198, s[12:13]
	global_load_ushort v167, v198, s[98:99]
	global_load_ushort v161, v178, s[12:13]
	global_load_ushort v163, v178, s[98:99]
	global_load_ushort v157, v179, s[12:13]
	global_load_ushort v159, v179, s[98:99]
	global_load_dwordx2 v[164:165], v[150:151], off
